# prep-phase pool-fold K loop: rolling 16-deep prefetch (same as down-proj instances)
# baseline (speedup 1.0000x reference)
.LBB0_191:
	s_or_b64 exec, exec, s[6:7]
	v_ashrrev_i32_e32 v15, 31, v14
	v_lshlrev_b64 v[16:17], 12, v[14:15]
	v_lshl_add_u64 v[16:17], s[48:49], 0, v[16:17]
	v_lshl_add_u64 v[16:17], v[200:201], 2, v[16:17]
	v_mov_b32_e32 v20, 0
	v_lshl_add_u64 v[16:17], v[16:17], 0, s[14:15]
	s_mov_b64 s[2:3], 0
	s_mov_b32 s6, s8
	v_mov_b32_e32 v21, v20
	v_mov_b32_e32 v18, v20
	v_mov_b32_e32 v19, v20
	s_waitcnt lgkmcnt(0)
	s_barrier
	s_mov_b32 s1, 0
	s_mov_b32 s0, 0x0
	v_lshl_add_u64 v[58:59], v[16:17], 0, s[0:1]
	v_mov_b64_e32 v[56:57], v[58:59]
	global_load_dword v40, v[56:57], off
	global_load_dword v41, v[56:57], off offset:2048
	s_mov_b32 s0, 0x1000
	v_lshl_add_u64 v[56:57], v[58:59], 0, s[0:1]
	global_load_dword v42, v[56:57], off
	global_load_dword v43, v[56:57], off offset:2048
	s_mov_b32 s0, 0x2000
	v_lshl_add_u64 v[56:57], v[58:59], 0, s[0:1]
	global_load_dword v44, v[56:57], off
	global_load_dword v45, v[56:57], off offset:2048
	s_mov_b32 s0, 0x3000
	v_lshl_add_u64 v[56:57], v[58:59], 0, s[0:1]
	global_load_dword v46, v[56:57], off
	global_load_dword v47, v[56:57], off offset:2048
	s_mov_b32 s0, 0x4000
	v_lshl_add_u64 v[56:57], v[58:59], 0, s[0:1]
	global_load_dword v48, v[56:57], off
	global_load_dword v49, v[56:57], off offset:2048
	s_mov_b32 s0, 0x5000
	v_lshl_add_u64 v[56:57], v[58:59], 0, s[0:1]
	global_load_dword v50, v[56:57], off
	global_load_dword v51, v[56:57], off offset:2048
	s_mov_b32 s0, 0x6000
	v_lshl_add_u64 v[56:57], v[58:59], 0, s[0:1]
	global_load_dword v52, v[56:57], off
	global_load_dword v53, v[56:57], off offset:2048
	s_mov_b32 s0, 0x7000
	v_lshl_add_u64 v[56:57], v[58:59], 0, s[0:1]
	global_load_dword v54, v[56:57], off
	global_load_dword v55, v[56:57], off offset:2048
.LBB0_192:
	s_add_u32 s2, s2, 0x8000
	s_addc_u32 s3, s3, 0
	v_lshl_add_u64 v[76:77], v[58:59], 0, s[2:3]
	v_mov_b32_e32 v23, s6
	ds_read2_b32 v[60:61], v23 offset0:0 offset1:1
	ds_read2_b32 v[62:63], v23 offset0:2 offset1:3
	ds_read2_b32 v[64:65], v23 offset0:4 offset1:5
	ds_read2_b32 v[66:67], v23 offset0:6 offset1:7
	ds_read2_b32 v[68:69], v23 offset0:128 offset1:129
	ds_read2_b32 v[70:71], v23 offset0:130 offset1:131
	ds_read2_b32 v[72:73], v23 offset0:132 offset1:133
	ds_read2_b32 v[74:75], v23 offset0:134 offset1:135
	s_add_i32 s6, s6, 32
	s_waitcnt lgkmcnt(0)
	s_waitcnt vmcnt(15)
	v_fma_f32 v20, v40, v60, v20
	v_fma_f32 v21, v40, v68, v21
	v_mov_b64_e32 v[56:57], v[76:77]
	global_load_dword v40, v[56:57], off
	s_waitcnt vmcnt(15)
	v_fma_f32 v18, v41, v60, v18
	v_fma_f32 v19, v41, v68, v19
	global_load_dword v41, v[56:57], off offset:2048
	s_waitcnt vmcnt(15)
	v_fma_f32 v20, v42, v61, v20
	v_fma_f32 v21, v42, v69, v21
	s_mov_b32 s0, 0x1000
	v_lshl_add_u64 v[56:57], v[76:77], 0, s[0:1]
	global_load_dword v42, v[56:57], off
	s_waitcnt vmcnt(15)
	v_fma_f32 v18, v43, v61, v18
	v_fma_f32 v19, v43, v69, v19
	global_load_dword v43, v[56:57], off offset:2048
	s_waitcnt vmcnt(15)
	v_fma_f32 v20, v44, v62, v20
	v_fma_f32 v21, v44, v70, v21
	s_mov_b32 s0, 0x2000
	v_lshl_add_u64 v[56:57], v[76:77], 0, s[0:1]
	global_load_dword v44, v[56:57], off
	s_waitcnt vmcnt(15)
	v_fma_f32 v18, v45, v62, v18
	v_fma_f32 v19, v45, v70, v19
	global_load_dword v45, v[56:57], off offset:2048
	s_waitcnt vmcnt(15)
	v_fma_f32 v20, v46, v63, v20
	v_fma_f32 v21, v46, v71, v21
	s_mov_b32 s0, 0x3000
	v_lshl_add_u64 v[56:57], v[76:77], 0, s[0:1]
	global_load_dword v46, v[56:57], off
	s_waitcnt vmcnt(15)
	v_fma_f32 v18, v47, v63, v18
	v_fma_f32 v19, v47, v71, v19
	global_load_dword v47, v[56:57], off offset:2048
	s_waitcnt vmcnt(15)
	v_fma_f32 v20, v48, v64, v20
	v_fma_f32 v21, v48, v72, v21
	s_mov_b32 s0, 0x4000
	v_lshl_add_u64 v[56:57], v[76:77], 0, s[0:1]
	global_load_dword v48, v[56:57], off
	s_waitcnt vmcnt(15)
	v_fma_f32 v18, v49, v64, v18
	v_fma_f32 v19, v49, v72, v19
	global_load_dword v49, v[56:57], off offset:2048
	s_waitcnt vmcnt(15)
	v_fma_f32 v20, v50, v65, v20
	v_fma_f32 v21, v50, v73, v21
	s_mov_b32 s0, 0x5000
	v_lshl_add_u64 v[56:57], v[76:77], 0, s[0:1]
	global_load_dword v50, v[56:57], off
	s_waitcnt vmcnt(15)
	v_fma_f32 v18, v51, v65, v18
	v_fma_f32 v19, v51, v73, v19
	global_load_dword v51, v[56:57], off offset:2048
	s_waitcnt vmcnt(15)
	v_fma_f32 v20, v52, v66, v20
	v_fma_f32 v21, v52, v74, v21
	s_mov_b32 s0, 0x6000
	v_lshl_add_u64 v[56:57], v[76:77], 0, s[0:1]
	global_load_dword v52, v[56:57], off
	s_waitcnt vmcnt(15)
	v_fma_f32 v18, v53, v66, v18
	v_fma_f32 v19, v53, v74, v19
	global_load_dword v53, v[56:57], off offset:2048
	s_waitcnt vmcnt(15)
	v_fma_f32 v20, v54, v67, v20
	v_fma_f32 v21, v54, v75, v21
	s_mov_b32 s0, 0x7000
	v_lshl_add_u64 v[56:57], v[76:77], 0, s[0:1]
	global_load_dword v54, v[56:57], off
	s_waitcnt vmcnt(15)
	v_fma_f32 v18, v55, v67, v18
	v_fma_f32 v19, v55, v75, v19
	global_load_dword v55, v[56:57], off offset:2048
	s_cmp_eq_u32 s2, 0x78000
	s_cbranch_scc0 .LBB0_192
	v_mov_b32_e32 v23, s6
	ds_read2_b32 v[60:61], v23 offset0:0 offset1:1
	ds_read2_b32 v[62:63], v23 offset0:2 offset1:3
	ds_read2_b32 v[64:65], v23 offset0:4 offset1:5
	ds_read2_b32 v[66:67], v23 offset0:6 offset1:7
	ds_read2_b32 v[68:69], v23 offset0:128 offset1:129
	ds_read2_b32 v[70:71], v23 offset0:130 offset1:131
	ds_read2_b32 v[72:73], v23 offset0:132 offset1:133
	ds_read2_b32 v[74:75], v23 offset0:134 offset1:135
	s_add_i32 s6, s6, 32
	s_waitcnt lgkmcnt(0)
	s_waitcnt vmcnt(15)
	v_fma_f32 v20, v40, v60, v20
	v_fma_f32 v21, v40, v68, v21
	s_waitcnt vmcnt(14)
	v_fma_f32 v18, v41, v60, v18
	v_fma_f32 v19, v41, v68, v19
	s_waitcnt vmcnt(13)
	v_fma_f32 v20, v42, v61, v20
	v_fma_f32 v21, v42, v69, v21
	s_waitcnt vmcnt(12)
	v_fma_f32 v18, v43, v61, v18
	v_fma_f32 v19, v43, v69, v19
	s_waitcnt vmcnt(11)
	v_fma_f32 v20, v44, v62, v20
	v_fma_f32 v21, v44, v70, v21
	s_waitcnt vmcnt(10)
	v_fma_f32 v18, v45, v62, v18
	v_fma_f32 v19, v45, v70, v19
	s_waitcnt vmcnt(9)
	v_fma_f32 v20, v46, v63, v20
	v_fma_f32 v21, v46, v71, v21
	s_waitcnt vmcnt(8)
	v_fma_f32 v18, v47, v63, v18
	v_fma_f32 v19, v47, v71, v19
	s_waitcnt vmcnt(7)
	v_fma_f32 v20, v48, v64, v20
	v_fma_f32 v21, v48, v72, v21
	s_waitcnt vmcnt(6)
	v_fma_f32 v18, v49, v64, v18
	v_fma_f32 v19, v49, v72, v19
	s_waitcnt vmcnt(5)
	v_fma_f32 v20, v50, v65, v20
	v_fma_f32 v21, v50, v73, v21
	s_waitcnt vmcnt(4)
	v_fma_f32 v18, v51, v65, v18
	v_fma_f32 v19, v51, v73, v19
	s_waitcnt vmcnt(3)
	v_fma_f32 v20, v52, v66, v20
	v_fma_f32 v21, v52, v74, v21
	s_waitcnt vmcnt(2)
	v_fma_f32 v18, v53, v66, v18
	v_fma_f32 v19, v53, v74, v19
	s_waitcnt vmcnt(1)
	v_fma_f32 v20, v54, v67, v20
	v_fma_f32 v21, v54, v75, v21
	s_waitcnt vmcnt(0)
	v_fma_f32 v18, v55, v67, v18
	v_fma_f32 v19, v55, v75, v19
	v_lshlrev_b64 v[14:15], 1, v[14:15]
	v_lshl_add_u64 v[16:17], v[10:11], 0, v[14:15]
	s_lshl_b32 s86, s86, 1
	v_cvt_pk_bf16_f32 v3, v20, v21
	v_lshl_add_u64 v[16:17], v[16:17], 0, s[86:87]
	v_lshl_add_u64 v[14:15], v[12:13], 0, v[14:15]
	s_add_i32 s4, s4, s5
	global_store_dword v[16:17], v3, off offset:1024
	v_cvt_pk_bf16_f32 v3, v18, v19
	v_lshl_add_u64 v[14:15], v[14:15], 0, s[86:87]
	s_cmpk_gt_i32 s4, 0xff
	global_store_dword v[14:15], v3, off offset:1024
	s_cbranch_scc0 .LBB0_187
	v_readlane_b32 s0, v254, 1
	s_mov_b32 s4, s0
	v_readlane_b32 s1, v254, 2
